# prep wave: bf16 unpack via d16_hi loads (30 shifts removed), tanh pre-multiply fused (bit-identical)
# baseline (speedup 1.0000x reference)
.LBB0_592:
	s_or_b64 exec, exec, s[36:37]
	v_readlane_b32 s0, v253, 40
	v_lshlrev_b32_e32 v64, 16, v111
	v_lshlrev_b32_e32 v65, 16, v112
	v_lshlrev_b32_e32 v66, 16, v113
	v_readlane_b32 s1, v253, 41
	s_waitcnt lgkmcnt(0)
	s_lshl_b32 s74, s15, 4
	s_mov_b32 s15, 0
	v_cndmask_b32_e64 v182, 0, v64, s[0:1]
	v_cndmask_b32_e64 v178, 0, v65, s[0:1]
	v_cndmask_b32_e64 v179, 0, v66, s[0:1]
	v_readlane_b32 s0, v253, 43
	v_lshlrev_b32_e32 v64, 16, v104
	v_lshlrev_b32_e32 v65, 16, v109
	v_lshlrev_b32_e32 v66, 16, v110
	v_readlane_b32 s1, v253, 44
	s_mov_b32 s82, 0
	s_nop 0
	v_cndmask_b32_e64 v181, 0, v64, s[0:1]
	v_cndmask_b32_e64 v180, 0, v65, s[0:1]
	v_cndmask_b32_e64 v104, 0, v66, s[0:1]
	v_readlane_b32 s0, v253, 45
	v_lshlrev_b32_e32 v64, 16, v105
	v_lshlrev_b32_e32 v65, 16, v106
	v_lshlrev_b32_e32 v66, 16, v108
	v_readlane_b32 s1, v253, 46
	s_nop 1
	v_cndmask_b32_e64 v177, 0, v64, s[0:1]
	v_cndmask_b32_e64 v105, 0, v65, s[0:1]
	v_cndmask_b32_e64 v106, 0, v66, s[0:1]
	v_readlane_b32 s0, v253, 48
	v_lshlrev_b32_e32 v64, 16, v102
	v_lshlrev_b32_e32 v65, 16, v103
	v_lshlrev_b32_e32 v66, 16, v107
	v_readlane_b32 s1, v253, 49
	s_nop 1
	v_cndmask_b32_e64 v175, 0, v64, s[0:1]
	v_cndmask_b32_e64 v107, 0, v65, s[0:1]
	v_cndmask_b32_e64 v108, 0, v66, s[0:1]
	v_readlane_b32 s0, v253, 51
	v_lshlrev_b32_e32 v64, 16, v99
	v_lshlrev_b32_e32 v65, 16, v100
	v_lshlrev_b32_e32 v66, 16, v101
	v_readlane_b32 s1, v253, 52
	s_nop 1
	v_cndmask_b32_e64 v174, 0, v64, s[0:1]
	v_cndmask_b32_e64 v109, 0, v65, s[0:1]
	v_cndmask_b32_e64 v110, 0, v66, s[0:1]
	v_readlane_b32 s0, v253, 54
	v_lshlrev_b32_e32 v64, 16, v98
	v_lshlrev_b32_e32 v65, 16, v115
	v_lshlrev_b32_e32 v66, 16, v133
	v_readlane_b32 s1, v253, 55
	v_or_b32_e32 v133, s14, v208
	v_lshl_add_u64 v[98:99], v[190:191], 0, s[74:75]
	v_cndmask_b32_e64 v173, 0, v64, s[0:1]
	v_cndmask_b32_e64 v111, 0, v65, s[0:1]
	v_cndmask_b32_e64 v112, 0, v66, s[0:1]
	v_readlane_b32 s0, v253, 57
	v_lshlrev_b32_e32 v64, 16, v94
	v_lshlrev_b32_e32 v65, 16, v95
	v_lshlrev_b32_e32 v66, 16, v114
	v_readlane_b32 s1, v253, 58
	s_mov_b32 s74, s61
	s_nop 0
	v_cndmask_b32_e64 v172, 0, v64, s[0:1]
	v_cndmask_b32_e64 v113, 0, v65, s[0:1]
	v_cndmask_b32_e64 v114, 0, v66, s[0:1]
	v_readlane_b32 s0, v253, 60
	v_lshlrev_b32_e32 v64, 16, v92
	v_lshlrev_b32_e32 v65, 16, v93
	v_lshlrev_b32_e32 v66, 16, v90
	v_readlane_b32 s1, v253, 61
	s_nop 1
	v_cndmask_b32_e64 v167, 0, v64, s[0:1]
	v_cndmask_b32_e64 v115, 0, v65, s[0:1]
	v_cndmask_b32_e64 v164, 0, v66, s[0:1]
	v_readlane_b32 s0, v253, 63
	s_waitcnt vmcnt(5)
	v_lshlrev_b32_e32 v64, 16, v91
	s_waitcnt vmcnt(4)
	v_lshlrev_b32_e32 v65, 16, v134
	s_waitcnt vmcnt(3)
	v_lshlrev_b32_e32 v66, 16, v135
	v_readlane_b32 s1, v252, 0
	s_nop 1
	v_cndmask_b32_e64 v169, 0, v64, s[0:1]
	v_cndmask_b32_e64 v168, 0, v65, s[0:1]
	v_cndmask_b32_e64 v166, 0, v66, s[0:1]
	v_readlane_b32 s0, v252, 2
	s_waitcnt vmcnt(2)
	v_lshlrev_b32_e32 v64, 16, v88
	s_waitcnt vmcnt(1)
	v_lshlrev_b32_e32 v65, 16, v89
	s_waitcnt vmcnt(0)
	v_lshlrev_b32_e32 v66, 16, v136
	v_readlane_b32 s1, v252, 3
	s_nop 1
	v_cndmask_b32_e64 v171, 0, v64, s[0:1]
	v_cndmask_b32_e64 v170, 0, v65, s[0:1]
	v_cndmask_b32_e64 v165, 0, v66, s[0:1]
	s_mov_b32 s0, 0
	v_mov_b32_e32 v134, 0
	v_mov_b32_e32 v135, 0
	v_mov_b32_e32 v136, 0
	v_mov_b32_e32 v137, 0
	v_mov_b32_e32 v138, 0
	v_mov_b32_e32 v139, 0
	v_mov_b32_e32 v140, 0
	v_mov_b32_e32 v141, 0
	v_mov_b32_e32 v142, 0
	v_mov_b32_e32 v143, 0
	v_mov_b32_e32 v144, 0
	v_mov_b32_e32 v145, 0
	v_mov_b32_e32 v146, 0
	v_mov_b32_e32 v147, 0
	v_mov_b32_e32 v148, 0
	v_mov_b32_e32 v149, 0
	v_mov_b32_e32 v150, 0
	v_mov_b32_e32 v151, 0
	v_mov_b32_e32 v152, 0
	v_mov_b32_e32 v153, 0
	v_mov_b32_e32 v154, 0
	v_mov_b32_e32 v155, 0
	v_mov_b32_e32 v156, 0
	v_mov_b32_e32 v157, 0
	v_mov_b32_e32 v158, 0
	v_mov_b32_e32 v159, 0
	v_mov_b32_e32 v160, 0
	v_mov_b32_e32 v161, 0
	v_mov_b32_e32 v162, 0
	v_mov_b32_e32 v163, 0
	s_branch .LBB0_595
.LBB0_593:
	s_or_b64 exec, exec, s[80:81]
	s_waitcnt vmcnt(29)
	s_nop 2
	s_waitcnt vmcnt(28)
	s_waitcnt vmcnt(27)
	s_cmp_lt_u32 s84, s62
	v_cndmask_b32_e32 v182, 0, v134, vcc
	v_cndmask_b32_e32 v178, 0, v135, vcc
	v_cndmask_b32_e32 v179, 0, v136, vcc
	s_waitcnt vmcnt(26)
	s_waitcnt vmcnt(25)
	s_waitcnt vmcnt(24)
	s_cselect_b64 vcc, -1, 0
	v_cndmask_b32_e32 v181, 0, v137, vcc
	v_cndmask_b32_e32 v180, 0, v138, vcc
	v_cndmask_b32_e32 v104, 0, v139, vcc
	s_waitcnt vmcnt(23)
	s_waitcnt vmcnt(22)
	s_waitcnt vmcnt(21)
	v_cndmask_b32_e64 v177, 0, v140, s[36:37]
	v_cndmask_b32_e64 v105, 0, v141, s[36:37]
	v_cndmask_b32_e64 v106, 0, v142, s[36:37]
	s_waitcnt vmcnt(20)
	s_waitcnt vmcnt(19)
	s_waitcnt vmcnt(18)
	v_cndmask_b32_e64 v175, 0, v143, s[38:39]
	v_cndmask_b32_e64 v107, 0, v144, s[38:39]
	v_cndmask_b32_e64 v108, 0, v145, s[38:39]
	s_waitcnt vmcnt(17)
	s_waitcnt vmcnt(16)
	s_waitcnt vmcnt(15)
	v_cndmask_b32_e64 v174, 0, v146, s[40:41]
	v_cndmask_b32_e64 v109, 0, v147, s[40:41]
	v_cndmask_b32_e64 v110, 0, v148, s[40:41]
	s_waitcnt vmcnt(14)
	s_waitcnt vmcnt(13)
	s_waitcnt vmcnt(12)
	v_cndmask_b32_e64 v173, 0, v149, s[42:43]
	v_cndmask_b32_e64 v111, 0, v150, s[42:43]
	v_cndmask_b32_e64 v112, 0, v151, s[42:43]
	s_waitcnt vmcnt(11)
	s_waitcnt vmcnt(10)
	s_waitcnt vmcnt(9)
	v_cndmask_b32_e64 v172, 0, v152, s[44:45]
	v_cndmask_b32_e64 v113, 0, v153, s[44:45]
	v_cndmask_b32_e64 v114, 0, v154, s[44:45]
	s_waitcnt vmcnt(8)
	s_waitcnt vmcnt(7)
	s_waitcnt vmcnt(6)
	v_cndmask_b32_e64 v167, 0, v155, s[46:47]
	v_cndmask_b32_e64 v115, 0, v156, s[46:47]
	v_cndmask_b32_e64 v164, 0, v157, s[46:47]
	s_waitcnt vmcnt(5)
	s_waitcnt vmcnt(4)
	s_waitcnt vmcnt(3)
	s_waitcnt lgkmcnt(0)
	v_cndmask_b32_e64 v169, 0, v158, s[48:49]
	v_cndmask_b32_e64 v168, 0, v159, s[48:49]
	v_cndmask_b32_e64 v166, 0, v160, s[48:49]
	s_waitcnt vmcnt(2)
	s_waitcnt vmcnt(1)
	s_waitcnt vmcnt(0)
	v_cndmask_b32_e64 v171, 0, v161, s[50:51]
	v_cndmask_b32_e64 v170, 0, v162, s[50:51]
	v_cndmask_b32_e64 v165, 0, v163, s[50:51]

.LBB0_597:
	s_andn2_b64 vcc, exec, s[36:37]
	s_cbranch_vccnz .LBB0_594
	ds_read2st64_b32 v[236:237], v210 offset1:1
	ds_read2st64_b32 v[238:239], v210 offset0:2 offset1:3
	ds_read2st64_b32 v[240:241], v210 offset0:4 offset1:5
	ds_read2st64_b32 v[242:243], v210 offset0:6 offset1:7
	ds_read2st64_b32 v[244:245], v210 offset0:8 offset1:9
	ds_read2st64_b32 v[246:247], v210 offset0:10 offset1:11
	ds_read2st64_b32 v[248:249], v210 offset0:12 offset1:13
	ds_read2st64_b32 v[250:251], v210 offset0:14 offset1:15
	s_add_i32 s83, s0, 1
	s_cmp_lt_u32 s83, s63
	s_cselect_b32 s0, s83, s0
	s_lshl_b32 s3, s0, 3
	s_sub_i32 s17, s61, s3
	s_and_b64 s[0:1], s[12:13], exec
	s_cselect_b32 s84, s3, s17
	s_add_i32 s3, s84, -1
	s_cmp_lt_u32 s3, s62
	s_cselect_b64 vcc, -1, 0
	s_and_b64 s[0:1], vcc, exec
	s_cselect_b32 s0, s3, s84
	s_add_i32 s0, s0, s14
	v_add_u32_e32 v64, s84, v133
	v_mad_i64_i32 v[100:101], s[0:1], s0, v212, v[96:97]
	v_ashrrev_i32_e32 v65, 31, v64
	s_add_i32 s0, s84, s14
	s_or_b32 s3, s84, 1
	v_lshlrev_b64 v[64:65], 11, v[64:65]
	s_cmp_lt_u32 s3, s62
	v_lshl_add_u64 v[72:73], v[200:201], 0, v[64:65]
	s_cselect_b64 s[36:37], -1, 0
	global_load_dwordx4 v[88:91], v[72:73], off offset:272
	global_load_dwordx4 v[92:95], v[72:73], off offset:256
	global_load_dwordx4 v[68:71], v[72:73], off offset:784
	global_load_dwordx4 v[84:87], v[72:73], off offset:768
	global_load_dwordx4 v[76:79], v[72:73], off offset:400
	global_load_dwordx4 v[80:83], v[72:73], off offset:384
	global_load_dwordx4 v[64:67], v[72:73], off offset:912
	s_nop 0
	global_load_dwordx4 v[72:75], v[72:73], off offset:896
	s_nop 0
	global_load_short_d16_hi v134, v[100:101], off
	global_load_short_d16_hi v135, v[100:101], off offset:128
	global_load_short_d16_hi v136, v[100:101], off offset:256
	v_mad_i64_i32 v[100:101], s[0:1], s0, v212, v[96:97]
	s_and_b64 s[0:1], s[36:37], exec
	s_cselect_b32 s0, s3, s84
	s_add_i32 s0, s0, s14
	s_or_b32 s3, s84, 2
	s_cmp_lt_u32 s3, s62
	s_cselect_b64 s[38:39], -1, 0
	global_load_short_d16_hi v137, v[100:101], off
	global_load_short_d16_hi v138, v[100:101], off offset:128
	global_load_short_d16_hi v139, v[100:101], off offset:256
	v_mad_i64_i32 v[100:101], s[0:1], s0, v212, v[96:97]
	s_and_b64 s[0:1], s[38:39], exec
	s_cselect_b32 s0, s3, s84
	s_add_i32 s0, s0, s14
	s_or_b32 s3, s84, 3
	s_cmp_lt_u32 s3, s62
	s_cselect_b64 s[40:41], -1, 0
	global_load_short_d16_hi v140, v[100:101], off
	global_load_short_d16_hi v141, v[100:101], off offset:128
	global_load_short_d16_hi v142, v[100:101], off offset:256
	v_mad_i64_i32 v[100:101], s[0:1], s0, v212, v[96:97]
	s_and_b64 s[0:1], s[40:41], exec
	s_cselect_b32 s0, s3, s84
	s_add_i32 s0, s0, s14
	s_or_b32 s3, s84, 4
	s_cmp_lt_u32 s3, s62
	s_cselect_b64 s[42:43], -1, 0
	global_load_short_d16_hi v143, v[100:101], off
	global_load_short_d16_hi v144, v[100:101], off offset:128
	global_load_short_d16_hi v145, v[100:101], off offset:256
	v_mad_i64_i32 v[100:101], s[0:1], s0, v212, v[96:97]
	s_and_b64 s[0:1], s[42:43], exec
	s_cselect_b32 s0, s3, s84
	s_add_i32 s0, s0, s14
	s_or_b32 s3, s84, 5
	s_cmp_lt_u32 s3, s62
	s_cselect_b64 s[44:45], -1, 0
	global_load_short_d16_hi v146, v[100:101], off
	global_load_short_d16_hi v147, v[100:101], off offset:128
	global_load_short_d16_hi v148, v[100:101], off offset:256
	v_mad_i64_i32 v[100:101], s[0:1], s0, v212, v[96:97]
	s_and_b64 s[0:1], s[44:45], exec
	s_cselect_b32 s0, s3, s84
	s_add_i32 s0, s0, s14
	s_or_b32 s3, s84, 6
	s_cmp_lt_u32 s3, s62
	s_cselect_b64 s[46:47], -1, 0
	global_load_short_d16_hi v149, v[100:101], off
	global_load_short_d16_hi v150, v[100:101], off offset:128
	global_load_short_d16_hi v151, v[100:101], off offset:256
	v_mad_i64_i32 v[100:101], s[0:1], s0, v212, v[96:97]
	s_and_b64 s[0:1], s[46:47], exec
	s_cselect_b32 s0, s3, s84
	s_add_i32 s0, s0, s14
	s_or_b32 s3, s84, 7
	s_cmp_lt_u32 s3, s62
	s_cselect_b64 s[48:49], -1, 0
	global_load_short_d16_hi v152, v[100:101], off
	global_load_short_d16_hi v153, v[100:101], off offset:128
	global_load_short_d16_hi v154, v[100:101], off offset:256
	v_mad_i64_i32 v[100:101], s[0:1], s0, v212, v[96:97]
	s_and_b64 s[0:1], s[48:49], exec
	s_cselect_b32 s0, s3, s84
	s_add_i32 s0, s0, s14
	s_add_i32 s3, s84, 8
	s_cmp_lt_u32 s3, s62
	s_cselect_b64 s[50:51], -1, 0
	global_load_short_d16_hi v155, v[100:101], off
	global_load_short_d16_hi v156, v[100:101], off offset:128
	global_load_short_d16_hi v157, v[100:101], off offset:256
	v_mad_i64_i32 v[100:101], s[0:1], s0, v212, v[96:97]
	s_and_b64 s[0:1], s[50:51], exec
	s_cselect_b32 s0, s3, s84
	s_add_i32 s0, s0, s14
	global_load_short_d16_hi v158, v[100:101], off
	global_load_short_d16_hi v159, v[100:101], off offset:128
	global_load_short_d16_hi v160, v[100:101], off offset:256
	v_mad_i64_i32 v[100:101], s[0:1], s0, v212, v[96:97]
	global_load_short_d16_hi v161, v[100:101], off
	global_load_short_d16_hi v162, v[100:101], off offset:128
	global_load_short_d16_hi v163, v[100:101], off offset:256
	v_mul_f32_e32 v102, v119, v180
	v_fmac_f32_e32 v102, v118, v178
	v_fmac_f32_e32 v102, v120, v105
	v_mul_f32_e32 v178, v125, v102
	v_mul_f32_e32 v100, v178, v178
	v_mov_b32_e32 v101, v185
	v_mul_f32_e32 v176, v116, v181
	v_fmac_f32_e32 v176, v124, v182
	v_mov_b32_dpp v101, v100 quad_perm:[1,0,3,2] row_mask:0xf bank_mask:0xf
	v_fmac_f32_e32 v101, v178, v178
	v_fmac_f32_e32 v176, v117, v177
	v_mov_b32_e32 v103, v185
	v_add_f32_dpp v100, v101, v101 quad_perm:[2,3,0,1] row_mask:0xf bank_mask:0xf bound_ctrl:1
	s_and_b64 s[0:1], s[12:13], exec
	s_cselect_b32 s21, s15, s74
	v_add_f32_dpp v100, v100, v100 row_half_mirror row_mask:0xf bank_mask:0xf bound_ctrl:1
	s_add_i32 s21, s21, s14
	s_nop 0
	v_add_f32_dpp v100, v100, v100 row_mirror row_mask:0xf bank_mask:0xf bound_ctrl:1
	s_nop 0
	v_readlane_b32 s85, v100, 0
	v_readlane_b32 s20, v100, 16
	v_readlane_b32 s18, v100, 32
	v_readlane_b32 s19, v100, 48
	s_waitcnt lgkmcnt(0)
	v_add_f32_e32 v101, v129, v237
	v_mul_f32_e32 v101, 0xbfb8aa3b, v101
	v_exp_f32_e32 v101, v101
	s_nop 0
	v_add_f32_e32 v101, 1.0, v101
	v_rcp_f32_e32 v183, v101
	s_nop 0
	v_add_f32_e32 v101, -1.0, v183
	v_fma_f32 v101, v126, v101, 1.0
	v_mul_f32_e32 v182, v102, v101
	v_mul_f32_e32 v101, v176, v182
	v_mul_f32_e32 v102, v127, v101
	s_nop 1
	v_mov_b32_dpp v103, v102 quad_perm:[1,0,3,2] row_mask:0xf bank_mask:0xf
	v_fmac_f32_e32 v103, v127, v101
	v_mov_b32_e32 v102, 0
	s_nop 0
	v_add_f32_dpp v101, v103, v103 quad_perm:[2,3,0,1] row_mask:0xf bank_mask:0xf bound_ctrl:1
	s_nop 1
	v_add_f32_dpp v101, v101, v101 row_half_mirror row_mask:0xf bank_mask:0xf bound_ctrl:1
	s_nop 1
	v_mov_b32_dpp v102, v101 row_mirror row_mask:0xf bank_mask:0xf
	s_and_saveexec_b64 s[80:81], s[10:11]
	s_cbranch_execz .LBB0_600
	s_ashr_i32 s1, s21, 31
	s_add_u32 s0, s21, s88
	s_addc_u32 s1, s1, 0
	s_lshl_b64 s[0:1], s[0:1], 9
	v_lshl_add_u64 v[202:203], v[98:99], 0, s[0:1]
	v_add_f32_e32 v101, v101, v102
	global_store_dword v[202:203], v101, off

.LBB0_614:
	s_or_b64 exec, exec, s[80:81]
	v_mov_b32_e32 v171, s64
	v_add_f32_e32 v171, s3, v171
	v_add_f32_e32 v171, s52, v171
	v_add_f32_e32 v171, s53, v171
	v_add_f32_e32 v171, 0x2b8cbccc, v171
	v_rsq_f32_e32 v171, v171
	v_mul_f32_e32 v166, v122, v166
	v_fmac_f32_e32 v166, v121, v164
	v_add_f32_e32 v114, v128, v250
	v_mul_f32_e32 v164, v168, v171
	v_mov_b32_e32 v171, s90
	v_add_f32_e32 v171, s78, v171
	v_add_f32_e32 v171, s79, v171
	v_add_f32_e32 v171, s17, v171
	v_add_f32_e32 v171, 0x2b8cbccc, v171
	v_rsq_f32_e32 v171, v171
	v_add_f32_e32 v100, v128, v236
	v_mul_f32_e32 v114, 0xbfb8aa3b, v114
	v_mul_f32_e32 v100, 0xbfb8aa3b, v100
	v_mul_f32_e32 v171, v215, v171
	v_mul_f32_e32 v215, v171, v216
	v_mov_b32_e32 v216, s35
	v_add_f32_e32 v216, s30, v216
	v_add_f32_e32 v216, s31, v216
	v_add_f32_e32 v216, s34, v216
	v_add_f32_e32 v216, 0x2b8cbccc, v216
	v_rsq_f32_e32 v216, v216
	v_exp_f32_e32 v114, v114
	v_add_f32_e32 v112, v128, v248
	v_add_f32_e32 v102, v128, v238
	v_mul_f32_e32 v213, v213, v216
	v_mov_b32_e32 v216, s29
	v_add_f32_e32 v216, s26, v216
	v_add_f32_e32 v216, s27, v216
	v_add_f32_e32 v216, s28, v216
	v_add_f32_e32 v216, 0x2b8cbccc, v216
	v_rsq_f32_e32 v216, v216
	v_exp_f32_e32 v100, v100
	v_fmac_f32_e32 v166, v123, v165
	v_mov_b32_e32 v165, s92
	v_mul_f32_e32 v202, v202, v216
	v_mov_b32_e32 v216, s25
	v_add_f32_e32 v216, s23, v216
	v_add_f32_e32 v216, s24, v216
	v_add_f32_e32 v216, s22, v216
	v_add_f32_e32 v216, 0x2b8cbccc, v216
	v_rsq_f32_e32 v216, v216
	v_mul_f32_e32 v112, 0xbfb8aa3b, v112
	v_mul_f32_e32 v102, 0xbfb8aa3b, v102
	v_mov_b32_e32 v170, s97
	v_mul_f32_e32 v180, v180, v216
	v_mov_b32_e32 v216, s20
	v_add_f32_e32 v216, s85, v216
	v_add_f32_e32 v165, s1, v165
	v_exp_f32_e32 v112, v112
	v_add_f32_e32 v110, v128, v246
	v_add_f32_e32 v104, v128, v240
	v_add_f32_e32 v216, s18, v216
	v_exp_f32_e32 v102, v102
	v_add_f32_e32 v170, s94, v170
	v_add_f32_e32 v165, s0, v165
	v_mul_f32_e32 v110, 0xbfb8aa3b, v110
	v_mul_f32_e32 v104, 0xbfb8aa3b, v104
	v_add_f32_e32 v216, s19, v216
	v_add_f32_e32 v170, s95, v170
	v_add_f32_e32 v114, 1.0, v114
	v_add_f32_e32 v165, s91, v165
	v_exp_f32_e32 v110, v110
	v_exp_f32_e32 v104, v104
	v_add_f32_e32 v216, 0x2b8cbccc, v216
	v_add_f32_e32 v100, 1.0, v100
	v_add_f32_e32 v170, s96, v170
	v_rcp_f32_e32 v114, v114
	v_add_f32_e32 v165, 0x2b8cbccc, v165
	v_rsq_f32_e32 v216, v216
	v_rcp_f32_e32 v100, v100
	v_add_f32_e32 v170, 0x2b8cbccc, v170
	v_rsq_f32_e32 v165, v165
	v_add_f32_e32 v112, 1.0, v112
	v_add_f32_e32 v102, 1.0, v102
	v_rsq_f32_e32 v170, v170
	v_rcp_f32_e32 v112, v112
	v_rcp_f32_e32 v102, v102
	v_add_f32_e32 v110, 1.0, v110
	v_add_f32_e32 v104, 1.0, v104
	v_mul_f32_e32 v114, 0x3f6002cd, v114
	v_rcp_f32_e32 v110, v110
	v_rcp_f32_e32 v104, v104
	v_mul_f32_e32 v178, v178, v216
	v_mul_f32_e32 v100, 0x3f6002cd, v100
	v_mul_f32_e32 v165, v217, v165
	v_mul_f32_e32 v183, v178, v183
	v_mul_f32_e32 v167, v164, v167
	v_cndmask_b32_e64 v216, v114, v100, s[12:13]
	v_mul_f32_e32 v170, v172, v170
	v_mul_f32_e32 v168, v165, v218
	v_mul_f32_e32 v112, 0x3f6002cd, v112
	v_mul_f32_e32 v102, 0x3f6002cd, v102
	v_cndmask_b32_e64 v217, v164, v178, s[12:13]
	v_cndmask_b32_e64 v218, v167, v183, s[12:13]
	v_cndmask_b32_e64 v220, v169, v176, s[12:13]
	v_cndmask_b32_e64 v100, v100, v114, s[12:13]
	v_cndmask_b32_e64 v114, v178, v164, s[12:13]
	v_cndmask_b32_e64 v164, v183, v167, s[12:13]
	v_cndmask_b32_e64 v167, v176, v169, s[12:13]
	v_add_f32_e32 v169, 0, v216
	v_mul_f32_e32 v172, v170, v219
	v_cndmask_b32_e64 v221, v112, v102, s[12:13]
	v_cndmask_b32_e64 v222, v170, v180, s[12:13]
	v_cndmask_b32_e64 v102, v102, v112, s[12:13]
	v_cndmask_b32_e64 v112, v180, v170, s[12:13]
	v_exp_f32_e32 v170, v169
	v_mul_f32_e32 v110, 0x3f6002cd, v110
	v_mul_f32_e32 v203, v202, v203
	v_mul_f32_e32 v184, v180, v184
	v_mul_f32_e32 v104, 0x3f6002cd, v104
	v_cndmask_b32_e64 v223, v172, v184, s[12:13]
	v_cndmask_b32_e64 v226, v110, v104, s[12:13]
	v_cndmask_b32_e64 v227, v165, v202, s[12:13]
	v_cndmask_b32_e64 v228, v168, v203, s[12:13]
	v_cndmask_b32_e64 v104, v104, v110, s[12:13]
	v_cndmask_b32_e64 v110, v202, v165, s[12:13]
	v_cndmask_b32_e64 v165, v203, v168, s[12:13]
	v_cndmask_b32_e64 v168, v184, v172, s[12:13]
	v_exp_f32_e64 v172, -v169
	v_readlane_b32 s0, v253, 22
	v_cndmask_b32_e64 v224, v113, v103, s[12:13]
	v_cndmask_b32_e64 v225, v173, v179, s[12:13]
	v_cndmask_b32_e64 v103, v103, v113, s[12:13]
	v_cndmask_b32_e64 v113, v179, v173, s[12:13]
	v_add_u32_e32 v173, s0, v101
	v_readlane_b32 s0, v253, 23
	v_cndmask_b32_e64 v219, v115, v182, s[12:13]
	v_cndmask_b32_e64 v229, v111, v105, s[12:13]
	v_cndmask_b32_e64 v230, v174, v181, s[12:13]
	v_cndmask_b32_e64 v105, v105, v111, s[12:13]
	v_cndmask_b32_e64 v111, v181, v174, s[12:13]
	ds_write_b32 v173, v217
	v_mul_f32_e32 v173, v218, v170
	v_add_u32_e32 v174, s0, v101
	v_readlane_b32 s0, v253, 24
	ds_write_b32 v174, v173
	v_mul_f32_e32 v170, v170, v219
	v_add_u32_e32 v173, s0, v101
	v_readlane_b32 s0, v253, 25
	ds_write_b32 v173, v170
	v_mul_f32_e32 v170, v220, v172
	v_add_u32_e32 v173, s0, v101
	v_add_f32_e32 v169, v221, v169
	v_add_f32_e32 v108, v128, v244
	v_add_f32_e32 v106, v128, v242
	ds_write_b32 v173, v170
	v_exp_f32_e32 v173, v169
	v_mul_f32_e32 v108, 0xbfb8aa3b, v108
	v_mul_f32_e32 v106, 0xbfb8aa3b, v106
	v_exp_f32_e32 v108, v108
	v_exp_f32_e32 v106, v106
	v_exp_f32_e64 v170, -v169
	v_readlane_b32 s0, v253, 26
	v_mul_f32_e32 v172, v222, v172
	v_add_f32_e32 v108, 1.0, v108
	v_add_u32_e32 v174, s0, v101
	v_readlane_b32 s0, v253, 27
	ds_write_b32 v174, v172
	v_mul_f32_e32 v172, v223, v173
	v_add_u32_e32 v174, s0, v101
	v_readlane_b32 s0, v253, 28
	ds_write_b32 v174, v172
	v_mul_f32_e32 v172, v224, v173
	v_add_u32_e32 v173, s0, v101
	v_readlane_b32 s0, v253, 29
	v_add_f32_e32 v106, 1.0, v106
	ds_write_b32 v173, v172
	v_mul_f32_e32 v172, v225, v170
	v_add_u32_e32 v173, s0, v101
	v_add_f32_e32 v169, v226, v169
	v_rcp_f32_e32 v108, v108
	v_rcp_f32_e32 v106, v106
	ds_write_b32 v173, v172
	v_exp_f32_e32 v173, v169
	v_exp_f32_e64 v172, -v169
	v_readlane_b32 s0, v253, 30
	v_mul_f32_e32 v170, v227, v170
	v_mul_f32_e32 v108, 0x3f6002cd, v108
	v_add_u32_e32 v174, s0, v101
	v_readlane_b32 s0, v253, 31
	v_mul_f32_e32 v106, 0x3f6002cd, v106
	ds_write_b32 v174, v170
	v_mul_f32_e32 v170, v228, v173
	v_add_u32_e32 v174, s0, v101
	v_readlane_b32 s0, v253, 32
	v_cndmask_b32_e64 v231, v108, v106, s[12:13]
	ds_write_b32 v174, v170
	v_mul_f32_e32 v170, v229, v173
	v_add_u32_e32 v173, s0, v101
	v_readlane_b32 s0, v253, 33
	ds_write_b32 v173, v170
	v_mul_f32_e32 v170, v230, v172
	v_add_u32_e32 v173, s0, v101
	v_add_f32_e32 v169, v231, v169
	ds_write_b32 v173, v170
	v_exp_f32_e32 v173, v169
	v_mul_f32_e32 v214, v213, v214
	v_cndmask_b32_e64 v232, v171, v213, s[12:13]
	v_exp_f32_e64 v170, -v169
	v_readlane_b32 s0, v253, 34
	v_cndmask_b32_e64 v233, v215, v214, s[12:13]
	v_mul_f32_e32 v172, v232, v172
	v_add_u32_e32 v174, s0, v101
	v_cndmask_b32_e64 v234, v109, v107, s[12:13]
	ds_write_b32 v174, v172
	v_mul_f32_e32 v172, v233, v173
	v_add_u32_e32 v174, s65, v101
	v_cndmask_b32_e64 v235, v175, v177, s[12:13]
	v_cndmask_b32_e64 v106, v106, v108, s[12:13]
	ds_write_b32 v174, v172
	v_mul_f32_e32 v172, v234, v173
	v_add_u32_e32 v173, s33, v101
	ds_write_b32 v173, v172
	v_mul_f32_e32 v172, v235, v170
	v_add_u32_e32 v173, s70, v101
	v_add_f32_e32 v106, v106, v169
	ds_write_b32 v173, v172
	v_exp_f32_e32 v172, v106
	v_cndmask_b32_e64 v108, v213, v171, s[12:13]
	v_exp_f32_e64 v169, -v106
	v_cndmask_b32_e64 v171, v214, v215, s[12:13]
	v_mul_f32_e32 v108, v108, v170
	v_add_u32_e32 v170, s71, v101
	v_cndmask_b32_e64 v107, v107, v109, s[12:13]
	ds_write_b32 v170, v108
	v_mul_f32_e32 v108, v171, v172
	v_add_u32_e32 v170, s66, v101
	v_cndmask_b32_e64 v109, v177, v175, s[12:13]
	ds_write_b32 v170, v108
	v_mul_f32_e32 v107, v107, v172
	v_add_u32_e32 v108, s67, v101
	ds_write_b32 v108, v107
	v_mul_f32_e32 v107, v109, v169
	v_add_u32_e32 v108, s93, v101
	v_add_f32_e32 v104, v104, v106
	ds_write_b32 v108, v107
	v_exp_f32_e32 v107, v104
	v_exp_f32_e64 v106, -v104
	v_mul_f32_e32 v108, v110, v169
	v_add_u32_e32 v109, s2, v101
	ds_write_b32 v109, v108
	v_mul_f32_e32 v108, v165, v107
	v_mul_f32_e32 v105, v105, v107
	v_add_u32_e32 v107, s89, v101
	ds_write_b32 v107, v105
	v_mul_f32_e32 v105, v111, v106
	v_add_u32_e32 v107, s76, v101
	v_add_f32_e32 v102, v102, v104
	ds_write_b32 v107, v105
	v_exp_f32_e32 v105, v102
	v_exp_f32_e64 v104, -v102
	v_add_f32_e32 v100, v100, v102
	v_mul_f32_e32 v106, v112, v106
	v_add_u32_e32 v107, s77, v101
	v_exp_f32_e64 v102, -v100
	v_exp_f32_e32 v100, v100
	ds_write_b32 v107, v106
	v_mul_f32_e32 v106, v168, v105
	v_mul_f32_e32 v103, v103, v105
	v_add_u32_e32 v105, s55, v101
	ds_write_b32 v105, v103
	v_mul_f32_e32 v103, v113, v104
	v_add_u32_e32 v105, s72, v101
	ds_write_b32 v105, v103
	v_mul_f32_e32 v103, v114, v104
	v_add_u32_e32 v104, s73, v101
	v_cndmask_b32_e64 v115, v182, v115, s[12:13]
	v_add_u32_e32 v109, s87, v101
	v_add_u32_e32 v107, s54, v101
	ds_write_b32 v104, v103
	v_mul_f32_e32 v103, v164, v100
	v_add_u32_e32 v104, s56, v101
	s_waitcnt vmcnt(36)
	s_nop 0
	s_nop 0
	ds_write_b32 v109, v108
	ds_write_b32 v107, v106
	ds_write_b32 v104, v103
	v_mul_f32_e32 v100, v115, v100
	v_add_u32_e32 v103, s57, v101
	v_mul_f32_e32 v92, 0xc038aa3b, v92
	v_mul_f32_e32 v88, 0xc038aa3b, v88
	ds_write_b32 v103, v100
	v_exp_f32_e32 v92, v92
	v_exp_f32_e32 v103, v88
	s_nop 0
	s_nop 0
	v_mul_f32_e32 v93, 0xc038aa3b, v93
	v_mul_f32_e32 v89, 0xc038aa3b, v89
	v_add_f32_e32 v88, 1.0, v92
	v_add_f32_e32 v92, 1.0, v103
	v_exp_f32_e32 v93, v93
	v_exp_f32_e32 v103, v89
	s_nop 0
	s_nop 0
	s_nop 0
	v_mul_f32_e32 v94, 0xc038aa3b, v94
	v_mul_f32_e32 v90, 0xc038aa3b, v90
	v_mul_f32_e32 v95, 0xc038aa3b, v95
	v_add_f32_e32 v89, 1.0, v93
	v_add_f32_e32 v93, 1.0, v103
	v_exp_f32_e32 v94, v94
	v_exp_f32_e32 v103, v90
	v_exp_f32_e32 v95, v95
	s_waitcnt vmcnt(32)
	s_nop 0
	s_nop 0
	v_mul_f32_e32 v81, 0xc038aa3b, v81
	v_mul_f32_e32 v77, 0xc038aa3b, v77
	s_nop 0
	v_cvt_pk_bf16_f32 v84, v84, v85
	v_cvt_pk_bf16_f32 v85, v86, v87
	v_exp_f32_e32 v81, v81
	v_exp_f32_e32 v86, v77
	v_mul_f32_e32 v91, 0xc038aa3b, v91
	v_add_f32_e32 v90, 1.0, v94
	v_add_f32_e32 v94, 1.0, v103
	v_exp_f32_e32 v103, v91
	v_add_f32_e32 v91, 1.0, v95
	s_nop 0
	s_nop 0
	v_rcp_f32_e32 v88, v88
	v_rcp_f32_e32 v92, v92
	v_rcp_f32_e32 v89, v89
	v_rcp_f32_e32 v93, v93
	v_rcp_f32_e32 v90, v90
	v_rcp_f32_e32 v91, v91
	v_mul_f32_e32 v82, 0xc038aa3b, v82
	v_mul_f32_e32 v78, 0xc038aa3b, v78
	v_add_f32_e32 v77, 1.0, v81
	v_add_f32_e32 v81, 1.0, v86
	v_exp_f32_e32 v82, v82
	v_exp_f32_e32 v86, v78
	s_nop 0
	s_nop 0
	s_nop 0
	s_nop 0
	v_pk_fma_f32 v[88:89], v[88:89], 2.0, -1.0 op_sel_hi:[1,0,0]
	v_pk_fma_f32 v[92:93], v[92:93], 2.0, -1.0 op_sel_hi:[1,0,0]
	v_pk_fma_f32 v[90:91], v[90:91], 2.0, -1.0 op_sel_hi:[1,0,0]
	v_mul_f32_e32 v80, 0xc038aa3b, v80
	v_mul_f32_e32 v76, 0xc038aa3b, v76
	v_mul_f32_e32 v83, 0xc038aa3b, v83
	v_mul_f32_e32 v79, 0xc038aa3b, v79
	v_add_f32_e32 v95, 1.0, v103
	v_cvt_pk_bf16_f32 v88, v88, v89
	v_cvt_pk_bf16_f32 v89, v90, v91
	v_cvt_pk_bf16_f32 v90, v92, v93
	v_exp_f32_e32 v80, v80
	v_exp_f32_e32 v92, v76
	v_add_f32_e32 v78, 1.0, v82
	v_add_f32_e32 v82, 1.0, v86
	v_exp_f32_e32 v83, v83
	v_exp_f32_e32 v86, v79
	v_rcp_f32_e32 v94, v94
	v_rcp_f32_e32 v95, v95
	v_add_f32_e32 v76, 1.0, v80
	v_add_f32_e32 v80, 1.0, v92
	v_add_f32_e32 v79, 1.0, v83
	v_add_f32_e32 v83, 1.0, v86
	v_pk_fma_f32 v[94:95], v[94:95], 2.0, -1.0 op_sel_hi:[1,0,0]
	v_rcp_f32_e32 v76, v76
	v_rcp_f32_e32 v80, v80
	v_rcp_f32_e32 v77, v77
	v_rcp_f32_e32 v81, v81
	v_rcp_f32_e32 v78, v78
	v_rcp_f32_e32 v82, v82
	v_rcp_f32_e32 v79, v79
	v_rcp_f32_e32 v83, v83
	v_cvt_pk_bf16_f32 v91, v94, v95
	v_cvt_pk_bf16_f32 v86, v68, v69
	v_cvt_pk_bf16_f32 v87, v70, v71
	v_pk_fma_f32 v[76:77], v[76:77], 2.0, -1.0 op_sel_hi:[1,0,0]
	v_pk_fma_f32 v[80:81], v[80:81], 2.0, -1.0 op_sel_hi:[1,0,0]
	v_pk_fma_f32 v[78:79], v[78:79], 2.0, -1.0 op_sel_hi:[1,0,0]
	v_pk_fma_f32 v[82:83], v[82:83], 2.0, -1.0 op_sel_hi:[1,0,0]
	v_cvt_pk_bf16_f32 v76, v76, v77
	v_cvt_pk_bf16_f32 v77, v78, v79
	v_cvt_pk_bf16_f32 v78, v80, v81
	v_cvt_pk_bf16_f32 v79, v82, v83
	s_waitcnt vmcnt(30)
	v_cvt_pk_bf16_f32 v68, v72, v73
	v_cvt_pk_bf16_f32 v69, v74, v75
	v_cvt_pk_bf16_f32 v70, v64, v65
	v_cvt_pk_bf16_f32 v71, v66, v67
	v_mfma_f32_16x16x32_bf16 v[80:83], v[88:91], v[0:3], 0
	v_mul_f32_e32 v100, v167, v102
	v_add_u32_e32 v104, s58, v101
	ds_write_b32 v104, v100
	ds_write2st64_b32 v101, v102, v166 offset1:47
	v_mfma_f32_16x16x32_bf16 v[64:67], v[84:87], v[32:35], 0
	s_waitcnt lgkmcnt(0)
	v_mfma_f32_16x16x32_bf16 v[80:83], v[76:79], v[16:19], v[80:83]
	v_mfma_f32_16x16x32_bf16 v[64:67], v[68:71], v[36:39], v[64:67]
	s_and_saveexec_b64 s[80:81], s[8:9]
	s_cbranch_execz .LBB0_616
	s_nop 5
	ds_write2st64_b32 v209, v80, v64 offset1:1
	ds_write2st64_b32 v209, v81, v65 offset0:2 offset1:3
	ds_write2st64_b32 v209, v82, v66 offset0:4 offset1:5
	ds_write2st64_b32 v209, v83, v67 offset0:6 offset1:7
